# GEMM loop first memory cluster: fragment reads and DMA loads ahead of the next-tile pointer selection scalar chain; one nop replaced by a scalar op
# baseline (speedup 1.0000x reference)
; #define PG8_STAGE(bufoff, gbase, voff) do { _Pragma("unroll") for (int _i = 0; _i < 2; ++_i) \
;         __builtin_amdgcn_global_load_lds((const unsigned*)((const char*)(gbase) + (voff)[_i]), (LAS unsigned*)(lds + (bufoff) + ldsw + _i * 8192), 16, 0, 0); } while (0)
; #define PG8_LDA(dst, b, h) do { _Pragma("unroll") for (int m = 0; m < 4; ++m) _Pragma("unroll") for (int k = 0; k < 2; ++k) dst[m][k] = *(const LAS h16x8*)(lds + PG8_SA(b, h) + aoff + m * 2048 + k * 1024); } while (0)
; #define PG8_LDB(dst, b, h) do { _Pragma("unroll") for (int n = 0; n < 2; ++n) _Pragma("unroll") for (int k = 0; k < 2; ++k) dst[n][k] = *(const LAS h16x8*)(lds + PG8_SB(b, h) + boff + n * 2048 + k * 1024); } while (0)
; #define PG8_MMA(ai, bj, At, Bt) do { __builtin_amdgcn_s_setprio(1); _Pragma("unroll") for (int m = 0; m < 4; ++m) _Pragma("unroll") for (int n = 0; n < 2; ++n) _Pragma("unroll") for (int k = 0; k < 2; ++k) \
;         acc[ai][bj][m][n] = __builtin_amdgcn_mfma_f32_16x16x32_f16(Bt[n][k], At[m][k], acc[ai][bj][m][n], 0, 0, 0); __builtin_amdgcn_s_setprio(0); } while (0)
; #define PG8_WAIT_L(n) asm volatile("s_waitcnt lgkmcnt(" #n ")" ::: "memory")
; #define PG8_BAR __builtin_amdgcn_s_barrier()
; #define PG8_SCHED __builtin_amdgcn_sched_barrier(0)
; __device__ __forceinline__ void gemm_phase(LAS unsigned char* lds, const Gemm g, const StaticOrder& S, const Epi& E) {
;     ...
;             const bool last = (t == nt - 2);
;             const char* a1 = cA + PG8_KOFF(t + 1);
;             const char* a2 = last ? nA : cA + PG8_KOFF(t + 2); const char* b2 = last ? nB : cB + (size_t)(t + 2) * kstep;
;             const char* a3 = a2 + kstep; const char* b3 = b2 + kstep;
;             PG8_LDB(B0, 0, 0); PG8_SCHED; PG8_LDA(At, 0, 0); PG8_STAGE(PG8_SA(1, 1), a1 + hstepA, voffA);
;             PG8_WAIT_L(8); PG8_BAR; PG8_WAIT_L(0); PG8_MMA(0, 0, At, B0); PG8_BAR; PG8_SCHED;
;             PG8_LDB(B1, 0, 1); PG8_STAGE(PG8_SB(0, 0), b2, voffB);
;             PG8_BAR; PG8_WAIT_L(0); PG8_MMA(0, 1, At, B1); PG8_BAR;
;             PG8_LDA(At, 0, 1); PG8_STAGE(PG8_SA(0, 0), a2, voffA);
;             PG8_BAR; PG8_WAIT_L(0); PG8_MMA(1, 0, At, B0); PG8_BAR; PG8_SCHED;
.Lprio_skip:
.LBB0_762:
	s_cmp_gt_u32 s34, 15
	s_cselect_b64 s[36:37], -1, 0
	s_and_b64 s[36:37], s[6:7], s[36:37]
	s_and_b64 s[36:37], s[36:37], exec
	s_cselect_b32 s42, 0xfffff000, 0
	s_cselect_b32 s43, -1, 0
	s_add_i32 s38, s34, 2
	ds_read_b128 v[128:131], v224
	ds_read_b128 v[132:135], v224 offset:1024
	ds_read_b128 v[136:139], v224 offset:2048
	ds_read_b128 v[140:143], v224 offset:3072
	s_add_u32 s86, s0, s42
	s_addc_u32 s87, s1, s43
	s_add_i32 m0, s58, 0xc000
	ds_read_b128 v[144:147], v239
	ds_read_b128 v[148:151], v239 offset:1024
	ds_read_b128 v[152:155], v239 offset:2048
	ds_read_b128 v[156:159], v239 offset:3072
	ds_read_b128 v[160:163], v239 offset:4096
	ds_read_b128 v[164:167], v239 offset:5120
	ds_read_b128 v[168:171], v239 offset:6144
	ds_read_b128 v[172:175], v239 offset:7168
	global_load_lds_dwordx4 v212, s[86:87]
	s_add_i32 m0, s58, 0xe000
	s_cmp_gt_u32 s34, 13
	global_load_lds_dwordx4 v214, s[86:87]
	s_cselect_b64 s[36:37], -1, 0
	s_and_b64 s[36:37], s[6:7], s[36:37]
	s_and_b64 s[36:37], s[36:37], exec
	s_cselect_b32 s36, 0xfffff000, 0
	s_cselect_b32 s35, -1, 0
	s_add_u32 s36, s0, s36
	s_addc_u32 s35, s1, s35
	s_add_u32 s36, s36, 0x80
	s_addc_u32 s35, s35, 0
	s_cmp_eq_u32 s66, s34
	s_cselect_b32 s34, s4, s36
	s_cselect_b32 s35, s5, s35
	s_cselect_b32 s37, s29, s33
	s_cselect_b32 s36, s28, s27
	s_waitcnt lgkmcnt(8)
	s_barrier
	s_waitcnt lgkmcnt(0)
	v_mfma_f32_16x16x32_f16 v[124:127], v[128:131], v[144:147], v[124:127]
	v_mfma_f32_16x16x32_f16 v[120:123], v[136:139], v[144:147], v[120:123]
	v_mfma_f32_16x16x32_f16 v[108:111], v[128:131], v[152:155], v[108:111]
	v_mfma_f32_16x16x32_f16 v[104:107], v[136:139], v[152:155], v[104:107]
	v_mfma_f32_16x16x32_f16 v[92:95], v[128:131], v[160:163], v[92:95]
	v_mfma_f32_16x16x32_f16 v[88:91], v[136:139], v[160:163], v[88:91]
	v_mfma_f32_16x16x32_f16 v[76:79], v[128:131], v[168:171], v[76:79]
	v_mfma_f32_16x16x32_f16 v[72:75], v[136:139], v[168:171], v[72:75]
	v_mfma_f32_16x16x32_f16 v[124:127], v[132:135], v[148:151], v[124:127]
	v_mfma_f32_16x16x32_f16 v[120:123], v[140:143], v[148:151], v[120:123]
	v_mfma_f32_16x16x32_f16 v[108:111], v[132:135], v[156:159], v[108:111]
	v_mfma_f32_16x16x32_f16 v[104:107], v[140:143], v[156:159], v[104:107]
	v_mfma_f32_16x16x32_f16 v[92:95], v[132:135], v[164:167], v[92:95]
	v_mfma_f32_16x16x32_f16 v[88:91], v[140:143], v[164:167], v[88:91]
	v_mfma_f32_16x16x32_f16 v[76:79], v[132:135], v[172:175], v[76:79]
	v_mfma_f32_16x16x32_f16 v[72:75], v[140:143], v[172:175], v[72:75]
	s_barrier
	s_add_u32 s86, s36, 0x80
	s_addc_u32 s87, s37, 0
	s_add_i32 m0, s31, 0x10000
	ds_read_b128 v[176:179], v225
	ds_read_b128 v[180:183], v225 offset:1024
	ds_read_b128 v[184:187], v225 offset:2048
	ds_read_b128 v[188:191], v225 offset:3072
	global_load_lds_dwordx4 v206, s[36:37]
	s_add_i32 m0, s31, 0x12000
	s_nop 0
	global_load_lds_dwordx4 v210, s[36:37]
	s_barrier
	s_waitcnt lgkmcnt(0)
	v_mfma_f32_16x16x32_f16 v[116:119], v[176:179], v[144:147], v[116:119]
	v_mfma_f32_16x16x32_f16 v[112:115], v[184:187], v[144:147], v[112:115]
	v_mfma_f32_16x16x32_f16 v[100:103], v[176:179], v[152:155], v[100:103]
	v_mfma_f32_16x16x32_f16 v[96:99], v[184:187], v[152:155], v[96:99]
	v_mfma_f32_16x16x32_f16 v[84:87], v[176:179], v[160:163], v[84:87]
	v_mfma_f32_16x16x32_f16 v[80:83], v[184:187], v[160:163], v[80:83]
	v_mfma_f32_16x16x32_f16 v[68:71], v[176:179], v[168:171], v[68:71]
	v_mfma_f32_16x16x32_f16 v[64:67], v[184:187], v[168:171], v[64:67]
	v_mfma_f32_16x16x32_f16 v[116:119], v[180:183], v[148:151], v[116:119]
	v_mfma_f32_16x16x32_f16 v[112:115], v[188:191], v[148:151], v[112:115]
	v_mfma_f32_16x16x32_f16 v[100:103], v[180:183], v[156:159], v[100:103]
	v_mfma_f32_16x16x32_f16 v[96:99], v[188:191], v[156:159], v[96:99]
	v_mfma_f32_16x16x32_f16 v[84:87], v[180:183], v[164:167], v[84:87]
	v_mfma_f32_16x16x32_f16 v[80:83], v[188:191], v[164:167], v[80:83]
	v_mfma_f32_16x16x32_f16 v[68:71], v[180:183], v[172:175], v[68:71]
	v_mfma_f32_16x16x32_f16 v[64:67], v[188:191], v[172:175], v[64:67]
	s_mov_b32 m0, s58
	s_add_u32 s88, s34, 0x80
	s_addc_u32 s89, s35, 0
	s_barrier
	ds_read_b128 v[144:147], v239 offset:16384
	ds_read_b128 v[148:151], v239 offset:17408
	ds_read_b128 v[152:155], v239 offset:18432
	ds_read_b128 v[156:159], v239 offset:19456
	ds_read_b128 v[160:163], v239 offset:20480
	ds_read_b128 v[164:167], v239 offset:21504
	ds_read_b128 v[168:171], v239 offset:22528
	ds_read_b128 v[172:175], v239 offset:23552
	global_load_lds_dwordx4 v204, s[34:35]
	s_mov_b32 m0, s59
	s_nop 0
	global_load_lds_dwordx4 v208, s[34:35]
	s_barrier
	s_waitcnt lgkmcnt(0)
	v_mfma_f32_16x16x32_f16 v[60:63], v[128:131], v[144:147], v[60:63]
	v_mfma_f32_16x16x32_f16 v[56:59], v[136:139], v[144:147], v[56:59]
	v_mfma_f32_16x16x32_f16 v[44:47], v[128:131], v[152:155], v[44:47]
	v_mfma_f32_16x16x32_f16 v[40:43], v[136:139], v[152:155], v[40:43]
	v_mfma_f32_16x16x32_f16 v[28:31], v[128:131], v[160:163], v[28:31]
	v_mfma_f32_16x16x32_f16 v[24:27], v[136:139], v[160:163], v[24:27]
	v_mfma_f32_16x16x32_f16 v[12:15], v[128:131], v[168:171], v[12:15]
	v_mfma_f32_16x16x32_f16 v[8:11], v[136:139], v[168:171], v[8:11]
	v_mfma_f32_16x16x32_f16 v[60:63], v[132:135], v[148:151], v[60:63]
	v_mfma_f32_16x16x32_f16 v[56:59], v[140:143], v[148:151], v[56:59]
	v_mfma_f32_16x16x32_f16 v[44:47], v[132:135], v[156:159], v[44:47]
	v_mfma_f32_16x16x32_f16 v[40:43], v[140:143], v[156:159], v[40:43]
	v_mfma_f32_16x16x32_f16 v[28:31], v[132:135], v[164:167], v[28:31]
	v_mfma_f32_16x16x32_f16 v[24:27], v[140:143], v[164:167], v[24:27]
	v_mfma_f32_16x16x32_f16 v[12:15], v[132:135], v[172:175], v[12:15]
	v_mfma_f32_16x16x32_f16 v[8:11], v[140:143], v[172:175], v[8:11]
	s_barrier
; #define PG8_STAGE(bufoff, gbase, voff) do { _Pragma("unroll") for (int _i = 0; _i < 2; ++_i) \
;         __builtin_amdgcn_global_load_lds((const unsigned*)((const char*)(gbase) + (voff)[_i]), (LAS unsigned*)(lds + (bufoff) + ldsw + _i * 8192), 16, 0, 0); } while (0)
; #define PG8_LDA(dst, b, h) do { _Pragma("unroll") for (int m = 0; m < 4; ++m) _Pragma("unroll") for (int k = 0; k < 2; ++k) dst[m][k] = *(const LAS h16x8*)(lds + PG8_SA(b, h) + aoff + m * 2048 + k * 1024); } while (0)
; #define PG8_LDB(dst, b, h) do { _Pragma("unroll") for (int n = 0; n < 2; ++n) _Pragma("unroll") for (int k = 0; k < 2; ++k) dst[n][k] = *(const LAS h16x8*)(lds + PG8_SB(b, h) + boff + n * 2048 + k * 1024); } while (0)
; #define PG8_MMA(ai, bj, At, Bt) do { __builtin_amdgcn_s_setprio(1); _Pragma("unroll") for (int m = 0; m < 4; ++m) _Pragma("unroll") for (int n = 0; n < 2; ++n) _Pragma("unroll") for (int k = 0; k < 2; ++k) \
;         acc[ai][bj][m][n] = __builtin_amdgcn_mfma_f32_16x16x32_f16(Bt[n][k], At[m][k], acc[ai][bj][m][n], 0, 0, 0); __builtin_amdgcn_s_setprio(0); } while (0)
; #define PG8_WAIT_V(n) asm volatile("s_waitcnt vmcnt(" #n ")" ::: "memory")
; #define PG8_WAIT_L(n) asm volatile("s_waitcnt lgkmcnt(" #n ")" ::: "memory")
; #define PG8_BAR __builtin_amdgcn_s_barrier()
; #define PG8_SCHED __builtin_amdgcn_sched_barrier(0)
; __device__ __forceinline__ void gemm_phase(LAS unsigned char* lds, const Gemm g, const StaticOrder& S, const Epi& E) {
;     ...
;             PG8_STAGE(PG8_SB(0, 1), b2 + hstepB, voffB);
;             PG8_WAIT_V(6); PG8_BAR; PG8_MMA(1, 1, At, B1); PG8_BAR;
;             PG8_LDB(B0, 1, 0); PG8_SCHED; PG8_LDA(At, 1, 0); PG8_STAGE(PG8_SA(0, 1), a2 + hstepA, voffA);
;             PG8_WAIT_L(8); PG8_BAR; PG8_WAIT_L(0); PG8_MMA(0, 0, At, B0); PG8_BAR; PG8_SCHED;
;             PG8_LDB(B1, 1, 1); PG8_STAGE(PG8_SB(1, 0), b3, voffB);
	s_add_u32 s36, s36, s18
	s_addc_u32 s37, s37, s19
	s_add_u32 s96, s36, 0x80
	s_addc_u32 s97, s37, 0
	s_add_i32 m0, s31, 0x14000
	s_nop 0
	global_load_lds_dwordx4 v206, s[36:37]
	s_add_i32 m0, s31, 0x16000
	s_nop 0
	global_load_lds_dwordx4 v210, s[36:37]
	s_waitcnt vmcnt(6)
	s_barrier
	v_mfma_f32_16x16x32_f16 v[52:55], v[176:179], v[144:147], v[52:55]
	v_mfma_f32_16x16x32_f16 v[48:51], v[184:187], v[144:147], v[48:51]
	v_mfma_f32_16x16x32_f16 v[36:39], v[176:179], v[152:155], v[36:39]
	v_mfma_f32_16x16x32_f16 v[32:35], v[184:187], v[152:155], v[32:35]
	v_mfma_f32_16x16x32_f16 v[20:23], v[176:179], v[160:163], v[20:23]
	v_mfma_f32_16x16x32_f16 v[16:19], v[184:187], v[160:163], v[16:19]
	v_mfma_f32_16x16x32_f16 v[4:7], v[176:179], v[168:171], v[4:7]
	v_mfma_f32_16x16x32_f16 v[0:3], v[184:187], v[168:171], v[0:3]
	v_mfma_f32_16x16x32_f16 v[52:55], v[180:183], v[148:151], v[52:55]
	v_mfma_f32_16x16x32_f16 v[48:51], v[188:191], v[148:151], v[48:51]
	v_mfma_f32_16x16x32_f16 v[36:39], v[180:183], v[156:159], v[36:39]
	v_mfma_f32_16x16x32_f16 v[32:35], v[188:191], v[156:159], v[32:35]
	v_mfma_f32_16x16x32_f16 v[20:23], v[180:183], v[164:167], v[20:23]
	v_mfma_f32_16x16x32_f16 v[16:19], v[188:191], v[164:167], v[16:19]
	v_mfma_f32_16x16x32_f16 v[4:7], v[180:183], v[172:175], v[4:7]
	v_mfma_f32_16x16x32_f16 v[0:3], v[188:191], v[172:175], v[0:3]
	s_barrier
	ds_read_b128 v[128:131], v241
	ds_read_b128 v[132:135], v241 offset:1024
	ds_read_b128 v[136:139], v241 offset:2048
	ds_read_b128 v[140:143], v241 offset:3072
	s_add_u32 s34, s34, s16
	s_addc_u32 s35, s35, s17
	s_mov_b32 m0, s60
	ds_read_b128 v[144:147], v239 offset:32768
	ds_read_b128 v[148:151], v239 offset:33792
	ds_read_b128 v[152:155], v239 offset:34816
	ds_read_b128 v[156:159], v239 offset:35840
	ds_read_b128 v[160:163], v239 offset:36864
	ds_read_b128 v[164:167], v239 offset:37888
	ds_read_b128 v[168:171], v239 offset:38912
	ds_read_b128 v[172:175], v239 offset:39936
	global_load_lds_dwordx4 v204, s[34:35]
	s_mov_b32 m0, s61
	s_nop 0
	global_load_lds_dwordx4 v208, s[34:35]
	s_waitcnt lgkmcnt(8)
	s_barrier
	s_waitcnt lgkmcnt(0)
	v_mfma_f32_16x16x32_f16 v[124:127], v[128:131], v[144:147], v[124:127]
	v_mfma_f32_16x16x32_f16 v[120:123], v[136:139], v[144:147], v[120:123]
	v_mfma_f32_16x16x32_f16 v[108:111], v[128:131], v[152:155], v[108:111]
	v_mfma_f32_16x16x32_f16 v[104:107], v[136:139], v[152:155], v[104:107]
	v_mfma_f32_16x16x32_f16 v[92:95], v[128:131], v[160:163], v[92:95]
	v_mfma_f32_16x16x32_f16 v[88:91], v[136:139], v[160:163], v[88:91]
	v_mfma_f32_16x16x32_f16 v[76:79], v[128:131], v[168:171], v[76:79]
	v_mfma_f32_16x16x32_f16 v[72:75], v[136:139], v[168:171], v[72:75]
	v_mfma_f32_16x16x32_f16 v[124:127], v[132:135], v[148:151], v[124:127]
	v_mfma_f32_16x16x32_f16 v[120:123], v[140:143], v[148:151], v[120:123]
	v_mfma_f32_16x16x32_f16 v[108:111], v[132:135], v[156:159], v[108:111]
	v_mfma_f32_16x16x32_f16 v[104:107], v[140:143], v[156:159], v[104:107]
	v_mfma_f32_16x16x32_f16 v[92:95], v[132:135], v[164:167], v[92:95]
	v_mfma_f32_16x16x32_f16 v[88:91], v[140:143], v[164:167], v[88:91]
	v_mfma_f32_16x16x32_f16 v[76:79], v[132:135], v[172:175], v[76:79]
	v_mfma_f32_16x16x32_f16 v[72:75], v[140:143], v[172:175], v[72:75]
	s_barrier
	s_add_i32 m0, s31, 0x18000
	ds_read_b128 v[176:179], v248
	ds_read_b128 v[180:183], v248 offset:1024
	ds_read_b128 v[184:187], v248 offset:2048
	ds_read_b128 v[188:191], v248 offset:3072
	global_load_lds_dwordx4 v206, s[86:87]
	s_add_i32 m0, s31, 0x1a000
	s_nop 0
	global_load_lds_dwordx4 v210, s[86:87]
	s_barrier
; #define PG8_STAGE(bufoff, gbase, voff) do { _Pragma("unroll") for (int _i = 0; _i < 2; ++_i) \
;         __builtin_amdgcn_global_load_lds((const unsigned*)((const char*)(gbase) + (voff)[_i]), (LAS unsigned*)(lds + (bufoff) + ldsw + _i * 8192), 16, 0, 0); } while (0)
; #define PG8_LDA(dst, b, h) do { _Pragma("unroll") for (int m = 0; m < 4; ++m) _Pragma("unroll") for (int k = 0; k < 2; ++k) dst[m][k] = *(const LAS h16x8*)(lds + PG8_SA(b, h) + aoff + m * 2048 + k * 1024); } while (0)
; #define PG8_MMA(ai, bj, At, Bt) do { __builtin_amdgcn_s_setprio(1); _Pragma("unroll") for (int m = 0; m < 4; ++m) _Pragma("unroll") for (int n = 0; n < 2; ++n) _Pragma("unroll") for (int k = 0; k < 2; ++k) \
;         acc[ai][bj][m][n] = __builtin_amdgcn_mfma_f32_16x16x32_f16(Bt[n][k], At[m][k], acc[ai][bj][m][n], 0, 0, 0); __builtin_amdgcn_s_setprio(0); } while (0)
; #define PG8_WAIT_V(n) asm volatile("s_waitcnt vmcnt(" #n ")" ::: "memory")
; #define PG8_WAIT_L(n) asm volatile("s_waitcnt lgkmcnt(" #n ")" ::: "memory")
; #define PG8_BAR __builtin_amdgcn_s_barrier()
; #define PG8_SCHED __builtin_amdgcn_sched_barrier(0)
; __device__ __forceinline__ void gemm_phase(LAS unsigned char* lds, const Gemm g, const StaticOrder& S, const Epi& E) {
;     ...
;             PG8_BAR; PG8_WAIT_L(0); PG8_MMA(0, 1, At, B1); PG8_BAR;
;             PG8_LDA(At, 1, 1); PG8_STAGE(PG8_SA(1, 0), a3, voffA);
;             PG8_BAR; PG8_WAIT_L(0); PG8_MMA(1, 0, At, B0); PG8_BAR; PG8_SCHED;
;             PG8_STAGE(PG8_SB(1, 1), b3 + hstepB, voffB);
;             PG8_WAIT_V(6); PG8_BAR; PG8_MMA(1, 1, At, B1); PG8_BAR;
;         }
;         E(acc, cur, wr, wc, fr, fq);
	s_waitcnt lgkmcnt(0)
	v_mfma_f32_16x16x32_f16 v[116:119], v[176:179], v[144:147], v[116:119]
	v_mfma_f32_16x16x32_f16 v[112:115], v[184:187], v[144:147], v[112:115]
	v_mfma_f32_16x16x32_f16 v[100:103], v[176:179], v[152:155], v[100:103]
	v_mfma_f32_16x16x32_f16 v[96:99], v[184:187], v[152:155], v[96:99]
	v_mfma_f32_16x16x32_f16 v[84:87], v[176:179], v[160:163], v[84:87]
	v_mfma_f32_16x16x32_f16 v[80:83], v[184:187], v[160:163], v[80:83]
	v_mfma_f32_16x16x32_f16 v[68:71], v[176:179], v[168:171], v[68:71]
	v_mfma_f32_16x16x32_f16 v[64:67], v[184:187], v[168:171], v[64:67]
	v_mfma_f32_16x16x32_f16 v[116:119], v[180:183], v[148:151], v[116:119]
	v_mfma_f32_16x16x32_f16 v[112:115], v[188:191], v[148:151], v[112:115]
	v_mfma_f32_16x16x32_f16 v[100:103], v[180:183], v[156:159], v[100:103]
	v_mfma_f32_16x16x32_f16 v[96:99], v[188:191], v[156:159], v[96:99]
	v_mfma_f32_16x16x32_f16 v[84:87], v[180:183], v[164:167], v[84:87]
	v_mfma_f32_16x16x32_f16 v[80:83], v[188:191], v[164:167], v[80:83]
	v_mfma_f32_16x16x32_f16 v[68:71], v[180:183], v[172:175], v[68:71]
	v_mfma_f32_16x16x32_f16 v[64:67], v[188:191], v[172:175], v[64:67]
	s_mov_b32 m0, s62
	s_barrier
	ds_read_b128 v[144:147], v239 offset:49152
	ds_read_b128 v[148:151], v239 offset:50176
	ds_read_b128 v[152:155], v239 offset:51200
	ds_read_b128 v[156:159], v239 offset:52224
	ds_read_b128 v[160:163], v239 offset:53248
	ds_read_b128 v[164:167], v239 offset:54272
	ds_read_b128 v[168:171], v239 offset:55296
	ds_read_b128 v[172:175], v239 offset:56320
	global_load_lds_dwordx4 v204, s[88:89]
	s_mov_b32 m0, s63
	s_nop 0
	global_load_lds_dwordx4 v208, s[88:89]
	s_barrier
	s_waitcnt lgkmcnt(0)
	v_mfma_f32_16x16x32_f16 v[60:63], v[128:131], v[144:147], v[60:63]
	v_mfma_f32_16x16x32_f16 v[56:59], v[136:139], v[144:147], v[56:59]
	v_mfma_f32_16x16x32_f16 v[44:47], v[128:131], v[152:155], v[44:47]
	v_mfma_f32_16x16x32_f16 v[40:43], v[136:139], v[152:155], v[40:43]
	v_mfma_f32_16x16x32_f16 v[28:31], v[128:131], v[160:163], v[28:31]
	v_mfma_f32_16x16x32_f16 v[24:27], v[136:139], v[160:163], v[24:27]
	v_mfma_f32_16x16x32_f16 v[12:15], v[128:131], v[168:171], v[12:15]
	v_mfma_f32_16x16x32_f16 v[8:11], v[136:139], v[168:171], v[8:11]
	v_mfma_f32_16x16x32_f16 v[60:63], v[132:135], v[148:151], v[60:63]
	v_mfma_f32_16x16x32_f16 v[56:59], v[140:143], v[148:151], v[56:59]
	v_mfma_f32_16x16x32_f16 v[44:47], v[132:135], v[156:159], v[44:47]
	v_mfma_f32_16x16x32_f16 v[40:43], v[140:143], v[156:159], v[40:43]
	v_mfma_f32_16x16x32_f16 v[28:31], v[132:135], v[164:167], v[28:31]
	v_mfma_f32_16x16x32_f16 v[24:27], v[140:143], v[164:167], v[24:27]
	v_mfma_f32_16x16x32_f16 v[12:15], v[132:135], v[172:175], v[12:15]
	v_mfma_f32_16x16x32_f16 v[8:11], v[140:143], v[172:175], v[8:11]
	s_barrier
	s_add_i32 m0, s31, 0x1c000
	s_nop 0
	global_load_lds_dwordx4 v206, s[96:97]
	s_add_i32 m0, s31, 0x1e000
	s_nop 0
	global_load_lds_dwordx4 v210, s[96:97]
	s_waitcnt vmcnt(6)
	s_barrier
	v_mfma_f32_16x16x32_f16 v[52:55], v[176:179], v[144:147], v[52:55]
	v_mfma_f32_16x16x32_f16 v[48:51], v[184:187], v[144:147], v[48:51]
	v_mfma_f32_16x16x32_f16 v[36:39], v[176:179], v[152:155], v[36:39]
	v_mfma_f32_16x16x32_f16 v[32:35], v[184:187], v[152:155], v[32:35]
	v_mfma_f32_16x16x32_f16 v[20:23], v[176:179], v[160:163], v[20:23]
	v_mfma_f32_16x16x32_f16 v[16:19], v[184:187], v[160:163], v[16:19]
	v_mfma_f32_16x16x32_f16 v[4:7], v[176:179], v[168:171], v[4:7]
	v_mfma_f32_16x16x32_f16 v[0:3], v[184:187], v[168:171], v[0:3]
	v_mfma_f32_16x16x32_f16 v[52:55], v[180:183], v[148:151], v[52:55]
	v_mfma_f32_16x16x32_f16 v[48:51], v[188:191], v[148:151], v[48:51]
	v_mfma_f32_16x16x32_f16 v[36:39], v[180:183], v[156:159], v[36:39]
	v_mfma_f32_16x16x32_f16 v[32:35], v[188:191], v[156:159], v[32:35]
	v_mfma_f32_16x16x32_f16 v[20:23], v[180:183], v[164:167], v[20:23]
	v_mfma_f32_16x16x32_f16 v[16:19], v[188:191], v[164:167], v[16:19]
	v_mfma_f32_16x16x32_f16 v[4:7], v[180:183], v[172:175], v[4:7]
	v_mfma_f32_16x16x32_f16 v[0:3], v[188:191], v[172:175], v[0:3]
	s_add_u32 s0, s0, 0x100
	s_addc_u32 s1, s1, 0
	s_add_u32 s27, s27, 0x100
	s_addc_u32 s33, s33, 0
	s_cmp_ge_u32 s38, s64
	s_mov_b32 s34, s38
	s_barrier
	s_cbranch_scc0 .LBB0_762
	s_setprio 0
	s_lshl_b32 s0, s84, 8
	s_or_b32 s27, s0, s65
	v_lshl_add_u32 v240, s30, 8, v200
	v_or_b32_e32 v216, s27, v202
	s_cmp_eq_u32 s93, 3
	s_cbranch_scc1 .Lst16_fast
	s_cmp_eq_u32 s93, 1
	s_cbranch_scc0 .Llora_no
	s_lshr_b32 s0, s84, 2
	s_cmp_lt_u32 s0, 2
	s_cbranch_scc1 .Llora_fast
